# hyena_prep: halo-row load retargeted to a free VGPR and its vmcnt(0) moved to the first consumer (no separate round trip before the 64 main loads)
# baseline (speedup 1.0000x reference)
; __device__ __forceinline__ unsigned pk2(float lo, float hi) { unsigned r; asm volatile("v_cvt_pk_bf16_f32 %0, %1, %2" : "=v"(r) : "v"(lo), "v"(hi)); return r; }
; __device__ __forceinline__ float bf2f(bf16_t v) { return __uint_as_float(((unsigned)v) << 16); }
; __device__ __forceinline__ void hyena_prep(const bf16_t* __restrict__ PA, const float* __restrict__ cb  , bf16_t* ZT0, bf16_t* G1T, bf16_t* G2T) {
;     ...
;         bf16_t raw[66];
; #pragma unroll
;         for (int k = 0; k < 66; ++k) { const int tt = t0 - 1 + k; raw[k] = (tt >= 0 && tt < L_) ? src[(size_t)tt * 3072] : (bf16_t)0; }
; #pragma unroll
;         for (int i8 = 0; i8 < 8; ++i8) {
;             float o[8];
; #pragma unroll
;             for (int k = 0; k < 8; ++k) o[k] = w0 * bf2f(raw[i8 * 8 + k]) + w1 * bf2f(raw[i8 * 8 + k + 1]) + w2 * bf2f(raw[i8 * 8 + k + 2]);
;             u32x4 w; w.x = pk2(o[0], o[1]); w.y = pk2(o[2], o[3]); w.z = pk2(o[4], o[5]); w.w = pk2(o[6], o[7]);
;             *(u32x4*)(dst + i8 * 8) = w;
;         }
.LBB0_215:
	s_waitcnt vmcnt(0)
	v_lshlrev_b32_e32 v12, 16, v243
	v_lshlrev_b32_e32 v78, 16, v13
	v_mov_b32_e32 v13, v78
	v_lshlrev_b32_e32 v27, 16, v27
	v_pk_mul_f32 v[12:13], v[8:9], v[12:13]
	s_waitcnt vmcnt(60)
	v_lshlrev_b32_e32 v79, 16, v30
	v_fma_f32 v12, v6, v27, v12
	v_lshlrev_b32_e32 v80, 16, v7
	v_add_f32_e32 v30, v12, v13
	v_pk_mul_f32 v[12:13], v[8:9], v[78:79]
	v_mov_b32_e32 v7, v9
	v_mov_b32_e32 v82, v78
	v_mov_b32_e32 v83, v80
	s_waitcnt vmcnt(59)
	v_lshlrev_b32_e32 v81, 16, v21
	v_pk_mul_f32 v[82:83], v[6:7], v[82:83]
	v_fma_f32 v12, v6, v80, v12
	v_fma_f32 v21, v8, v27, v82
	v_add_f32_e32 v27, v12, v13
	v_pk_mul_f32 v[12:13], v[8:9], v[80:81]
	s_cmp_eq_u32 s2, 1
	v_fma_f32 v12, v6, v79, v12
	v_add_f32_e32 v77, v12, v13
	s_waitcnt vmcnt(56)
	v_lshlrev_b32_e32 v13, 16, v17
	v_lshlrev_b32_e32 v12, 16, v10
	v_pk_mov_b32 v[78:79], v[78:79], v[12:13] op_sel:[1,0]
	s_mov_b32 s2, 0x28b1c000
	v_pk_mul_f32 v[78:79], v[8:9], v[78:79]
	v_lshlrev_b32_e32 v82, 16, v1
	v_fma_f32 v10, v6, v81, v78
	v_add_f32_e32 v10, v10, v79
	v_pk_mul_f32 v[78:79], v[8:9], v[12:13]
	s_cselect_b32 s2, s2, 0x29b1c000
	s_cmpk_gt_u32 s1, 0xff
	v_add_f32_e32 v21, v21, v83
	s_waitcnt vmcnt(55)
	v_lshlrev_b32_e32 v83, 16, v51
	v_fma_f32 v17, v6, v82, v78
	s_cselect_b32 s20, s2, 0x25b1c000
	v_mov_b32_e32 v84, v12
	v_mov_b32_e32 v85, v82
	v_add_f32_e32 v17, v17, v79
	v_pk_mul_f32 v[78:79], v[8:9], v[82:83]
	v_lshl_add_u64 v[14:15], v[4:5], 0, s[20:21]
	s_lshl_b32 s20, s3, 1
	v_pk_mul_f32 v[84:85], v[6:7], v[84:85]
	v_fma_f32 v51, v6, v13, v78
	v_lshl_add_u64 v[14:15], v[14:15], 0, s[20:21]
	v_fma_f32 v1, v8, v81, v84
	v_add_f32_e32 v51, v51, v79
	v_cvt_pk_bf16_f32 v78, v30, v21
	v_cvt_pk_bf16_f32 v79, v27, v77
	v_add_f32_e32 v1, v1, v85
	v_cvt_pk_bf16_f32 v80, v10, v1
	v_cvt_pk_bf16_f32 v81, v17, v51
	global_store_dwordx4 v[14:15], v[78:81], off
	s_waitcnt vmcnt(54)
	v_lshlrev_b32_e32 v24, 16, v24
	s_waitcnt vmcnt(52)
	v_lshlrev_b32_e32 v25, 16, v25
	v_lshlrev_b32_e32 v79, 16, v35
	v_lshlrev_b32_e32 v78, 16, v31
	v_pk_mov_b32 v[12:13], v[12:13], v[78:79] op_sel:[1,0]
	v_pk_mov_b32 v[30:31], v[82:83], v[24:25] op_sel:[1,0]
	v_pk_mul_f32 v[12:13], v[8:9], v[12:13]
	v_pk_mul_f32 v[30:31], v[8:9], v[30:31]
	v_fma_f32 v1, v6, v83, v12
	v_add_f32_e32 v1, v1, v13
	v_pk_mul_f32 v[12:13], v[8:9], v[78:79]
	v_fma_f32 v10, v6, v78, v30
	v_fma_f32 v12, v6, v24, v12
	v_add_f32_e32 v27, v12, v13
	v_pk_mul_f32 v[12:13], v[8:9], v[24:25]
	s_waitcnt vmcnt(50)
	v_lshlrev_b32_e32 v16, 16, v16
	v_fma_f32 v12, v6, v79, v12
	v_add_f32_e32 v24, v12, v13
	s_waitcnt vmcnt(49)
	v_lshlrev_b32_e32 v13, 16, v20
	v_lshlrev_b32_e32 v12, 16, v18
	v_pk_mov_b32 v[20:21], v[78:79], v[12:13] op_sel:[1,0]
	v_add_f32_e32 v10, v10, v31
	v_pk_mul_f32 v[20:21], v[8:9], v[20:21]
	v_mov_b32_e32 v30, v12
	v_fma_f32 v17, v6, v25, v20
	v_add_f32_e32 v18, v17, v21
	v_pk_mul_f32 v[20:21], v[8:9], v[12:13]
	v_mov_b32_e32 v31, v16
	s_waitcnt vmcnt(48)
	v_lshlrev_b32_e32 v17, 16, v59
	v_pk_mul_f32 v[30:31], v[6:7], v[30:31]
	v_fma_f32 v20, v6, v16, v20
	v_fma_f32 v25, v8, v25, v30
	v_add_f32_e32 v30, v20, v21
	v_pk_mul_f32 v[20:21], v[8:9], v[16:17]
	v_add_f32_e32 v25, v25, v31
	v_fma_f32 v20, v6, v13, v20
	v_add_f32_e32 v20, v20, v21
	v_cvt_pk_bf16_f32 v78, v1, v10
	v_cvt_pk_bf16_f32 v79, v27, v24
	v_cvt_pk_bf16_f32 v80, v18, v25
	v_cvt_pk_bf16_f32 v81, v30, v20
	s_waitcnt vmcnt(45)
	v_lshlrev_b32_e32 v21, 16, v42
	v_lshlrev_b32_e32 v20, 16, v38
	v_pk_mov_b32 v[12:13], v[12:13], v[20:21] op_sel:[1,0]
	v_lshlrev_b32_e32 v24, 16, v32
	v_pk_mul_f32 v[12:13], v[8:9], v[12:13]
	s_waitcnt vmcnt(44)
	v_lshlrev_b32_e32 v25, 16, v33
	v_fma_f32 v1, v6, v17, v12
	v_add_f32_e32 v1, v1, v13
	v_pk_mul_f32 v[12:13], v[8:9], v[20:21]
	v_pk_mov_b32 v[16:17], v[16:17], v[24:25] op_sel:[1,0]
	v_fma_f32 v12, v6, v24, v12
	v_add_f32_e32 v27, v12, v13
	v_pk_mul_f32 v[12:13], v[8:9], v[24:25]
	v_pk_mul_f32 v[16:17], v[8:9], v[16:17]
	v_fma_f32 v12, v6, v21, v12
	v_fma_f32 v10, v6, v20, v16
	v_add_f32_e32 v24, v12, v13
	s_waitcnt vmcnt(41)
	v_lshlrev_b32_e32 v13, 16, v26
	v_lshlrev_b32_e32 v12, 16, v22
	v_add_f32_e32 v10, v10, v17
	v_pk_mov_b32 v[16:17], v[20:21], v[12:13] op_sel:[1,0]
	v_lshlrev_b32_e32 v20, 16, v19
	v_pk_mul_f32 v[16:17], v[8:9], v[16:17]
	v_mov_b32_e32 v18, v12
	v_fma_f32 v16, v6, v25, v16
	v_mov_b32_e32 v19, v20
	v_add_f32_e32 v22, v16, v17
	v_pk_mul_f32 v[16:17], v[8:9], v[12:13]
	v_pk_mul_f32 v[18:19], v[6:7], v[18:19]
	s_waitcnt vmcnt(40)
	v_lshlrev_b32_e32 v21, 16, v67
	v_fma_f32 v18, v8, v25, v18
	v_fma_f32 v16, v6, v20, v16
	v_add_f32_e32 v18, v18, v19
	v_add_f32_e32 v19, v16, v17
	v_pk_mul_f32 v[16:17], v[8:9], v[20:21]
	global_store_dwordx4 v[14:15], v[78:81], off offset:16
	v_fma_f32 v16, v6, v13, v16
	v_add_f32_e32 v25, v16, v17
	v_cvt_pk_bf16_f32 v16, v1, v10
	v_cvt_pk_bf16_f32 v17, v27, v24
	v_cvt_pk_bf16_f32 v18, v22, v18
	v_cvt_pk_bf16_f32 v19, v19, v25
	global_store_dwordx4 v[14:15], v[16:19], off offset:32
	s_add_i32 s1, s1, s16
	s_add_i32 s0, s0, s49
	s_waitcnt vmcnt(39)
	v_lshlrev_b32_e32 v17, 16, v49
	v_lshlrev_b32_e32 v16, 16, v45
	v_pk_mov_b32 v[12:13], v[12:13], v[16:17] op_sel:[1,0]
	v_lshlrev_b32_e32 v18, 16, v39
	v_pk_mul_f32 v[12:13], v[8:9], v[12:13]
	s_waitcnt vmcnt(38)
	v_lshlrev_b32_e32 v19, 16, v40
	v_fma_f32 v1, v6, v21, v12
	v_add_f32_e32 v1, v1, v13
	v_pk_mul_f32 v[12:13], v[8:9], v[16:17]
	v_pk_mov_b32 v[20:21], v[20:21], v[18:19] op_sel:[1,0]
	v_fma_f32 v12, v6, v18, v12
	v_add_f32_e32 v24, v12, v13
	v_pk_mul_f32 v[12:13], v[8:9], v[18:19]
	v_pk_mul_f32 v[20:21], v[8:9], v[20:21]
	v_fma_f32 v12, v6, v17, v12
	v_add_f32_e32 v18, v12, v13
	s_waitcnt vmcnt(35)
; __device__ __forceinline__ unsigned pk2(float lo, float hi) { unsigned r; asm volatile("v_cvt_pk_bf16_f32 %0, %1, %2" : "=v"(r) : "v"(lo), "v"(hi)); return r; }
; __device__ __forceinline__ float bf2f(bf16_t v) { return __uint_as_float(((unsigned)v) << 16); }
; __device__ __forceinline__ void hyena_prep(const bf16_t* __restrict__ PA, const float* __restrict__ cb  , bf16_t* ZT0, bf16_t* G1T, bf16_t* G2T) {
;     ...
;         for (int i8 = 0; i8 < 8; ++i8) {
;             float o[8];
; #pragma unroll
;             for (int k = 0; k < 8; ++k) o[k] = w0 * bf2f(raw[i8 * 8 + k]) + w1 * bf2f(raw[i8 * 8 + k + 1]) + w2 * bf2f(raw[i8 * 8 + k + 2]);
;             u32x4 w; w.x = pk2(o[0], o[1]); w.y = pk2(o[2], o[3]); w.z = pk2(o[4], o[5]); w.w = pk2(o[6], o[7]);
;             *(u32x4*)(dst + i8 * 8) = w;
;         }
	v_lshlrev_b32_e32 v13, 16, v34
	v_lshlrev_b32_e32 v12, 16, v28
	v_fma_f32 v10, v6, v16, v20
	v_pk_mov_b32 v[16:17], v[16:17], v[12:13] op_sel:[1,0]
	v_lshlrev_b32_e32 v20, 16, v23
	v_pk_mul_f32 v[16:17], v[8:9], v[16:17]
	v_mov_b32_e32 v22, v12
	v_fma_f32 v16, v6, v19, v16
	v_add_f32_e32 v25, v16, v17
	v_pk_mul_f32 v[16:17], v[8:9], v[12:13]
	v_mov_b32_e32 v23, v20
	v_add_f32_e32 v10, v10, v21
	s_waitcnt vmcnt(34)
	v_lshlrev_b32_e32 v21, 16, v71
	v_pk_mul_f32 v[22:23], v[6:7], v[22:23]
	v_fma_f32 v16, v6, v20, v16
	v_fma_f32 v19, v8, v19, v22
	v_add_f32_e32 v22, v16, v17
	v_pk_mul_f32 v[16:17], v[8:9], v[20:21]
	v_add_f32_e32 v19, v19, v23
	v_fma_f32 v16, v6, v13, v16
	v_add_f32_e32 v23, v16, v17
	v_cvt_pk_bf16_f32 v16, v1, v10
	v_cvt_pk_bf16_f32 v17, v24, v18
	v_cvt_pk_bf16_f32 v18, v25, v19
	v_cvt_pk_bf16_f32 v19, v22, v23
	global_store_dwordx4 v[14:15], v[16:19], off offset:48
	s_cmpk_lt_i32 s1, 0x300
	s_waitcnt vmcnt(32)
	v_lshlrev_b32_e32 v17, 16, v57
	v_lshlrev_b32_e32 v16, 16, v52
	v_pk_mov_b32 v[12:13], v[12:13], v[16:17] op_sel:[1,0]
	v_lshlrev_b32_e32 v18, 16, v46
	v_pk_mul_f32 v[12:13], v[8:9], v[12:13]
	s_waitcnt vmcnt(31)
	v_lshlrev_b32_e32 v19, 16, v47
	v_fma_f32 v1, v6, v21, v12
	v_add_f32_e32 v1, v1, v13
	v_pk_mul_f32 v[12:13], v[8:9], v[16:17]
	v_pk_mov_b32 v[20:21], v[20:21], v[18:19] op_sel:[1,0]
	v_fma_f32 v12, v6, v18, v12
	v_add_f32_e32 v24, v12, v13
	v_pk_mul_f32 v[12:13], v[8:9], v[18:19]
	v_pk_mul_f32 v[20:21], v[8:9], v[20:21]
	v_fma_f32 v12, v6, v17, v12
	v_add_f32_e32 v18, v12, v13
	s_waitcnt vmcnt(28)
	v_lshlrev_b32_e32 v13, 16, v41
	v_lshlrev_b32_e32 v12, 16, v36
	v_fma_f32 v10, v6, v16, v20
	v_pk_mov_b32 v[16:17], v[16:17], v[12:13] op_sel:[1,0]
	v_lshlrev_b32_e32 v20, 16, v29
	v_pk_mul_f32 v[16:17], v[8:9], v[16:17]
	v_mov_b32_e32 v22, v12
	v_fma_f32 v16, v6, v19, v16
	v_add_f32_e32 v25, v16, v17
	v_pk_mul_f32 v[16:17], v[8:9], v[12:13]
	v_mov_b32_e32 v23, v20
	v_add_f32_e32 v10, v10, v21
	s_waitcnt vmcnt(27)
	v_lshlrev_b32_e32 v21, 16, v74
	v_pk_mul_f32 v[22:23], v[6:7], v[22:23]
	v_fma_f32 v16, v6, v20, v16
	v_fma_f32 v19, v8, v19, v22
	v_add_f32_e32 v22, v16, v17
	v_pk_mul_f32 v[16:17], v[8:9], v[20:21]
	v_add_f32_e32 v19, v19, v23
	v_fma_f32 v16, v6, v13, v16
	v_add_f32_e32 v23, v16, v17
	v_cvt_pk_bf16_f32 v16, v1, v10
	v_cvt_pk_bf16_f32 v17, v24, v18
	v_cvt_pk_bf16_f32 v18, v25, v19
	v_cvt_pk_bf16_f32 v19, v22, v23
	global_store_dwordx4 v[14:15], v[16:19], off offset:64
	s_waitcnt vmcnt(25)
	s_nop 0
	v_lshlrev_b32_e32 v17, 16, v63
	v_lshlrev_b32_e32 v16, 16, v60
	v_pk_mov_b32 v[12:13], v[12:13], v[16:17] op_sel:[1,0]
	v_lshlrev_b32_e32 v18, 16, v53
	v_pk_mul_f32 v[12:13], v[8:9], v[12:13]
	s_waitcnt vmcnt(24)
	v_lshlrev_b32_e32 v19, 16, v54
	v_fma_f32 v1, v6, v21, v12
	v_add_f32_e32 v1, v1, v13
	v_pk_mul_f32 v[12:13], v[8:9], v[16:17]
	v_pk_mov_b32 v[20:21], v[20:21], v[18:19] op_sel:[1,0]
	v_fma_f32 v12, v6, v18, v12
	v_add_f32_e32 v24, v12, v13
	v_pk_mul_f32 v[12:13], v[8:9], v[18:19]
	v_pk_mul_f32 v[20:21], v[8:9], v[20:21]
	v_fma_f32 v12, v6, v17, v12
	v_add_f32_e32 v18, v12, v13
	s_waitcnt vmcnt(21)
	v_lshlrev_b32_e32 v13, 16, v48
	v_lshlrev_b32_e32 v12, 16, v43
	v_fma_f32 v10, v6, v16, v20
	v_pk_mov_b32 v[16:17], v[16:17], v[12:13] op_sel:[1,0]
	v_lshlrev_b32_e32 v20, 16, v37
	v_pk_mul_f32 v[16:17], v[8:9], v[16:17]
	v_mov_b32_e32 v22, v12
	v_fma_f32 v16, v6, v19, v16
	v_add_f32_e32 v25, v16, v17
	v_pk_mul_f32 v[16:17], v[8:9], v[12:13]
	v_mov_b32_e32 v23, v20
	v_add_f32_e32 v10, v10, v21
	s_waitcnt vmcnt(20)
	v_lshlrev_b32_e32 v21, 16, v75
	v_pk_mul_f32 v[22:23], v[6:7], v[22:23]
	v_fma_f32 v16, v6, v20, v16
	v_fma_f32 v19, v8, v19, v22
	v_add_f32_e32 v22, v16, v17
	v_pk_mul_f32 v[16:17], v[8:9], v[20:21]
	v_add_f32_e32 v19, v19, v23
	v_fma_f32 v16, v6, v13, v16
	v_add_f32_e32 v23, v16, v17
	v_cvt_pk_bf16_f32 v16, v1, v10
	v_cvt_pk_bf16_f32 v17, v24, v18
	v_cvt_pk_bf16_f32 v18, v25, v19
	v_cvt_pk_bf16_f32 v19, v22, v23
	global_store_dwordx4 v[14:15], v[16:19], off offset:80
	s_waitcnt vmcnt(18)
; __device__ __forceinline__ unsigned pk2(float lo, float hi) { unsigned r; asm volatile("v_cvt_pk_bf16_f32 %0, %1, %2" : "=v"(r) : "v"(lo), "v"(hi)); return r; }
; __device__ __forceinline__ float bf2f(bf16_t v) { return __uint_as_float(((unsigned)v) << 16); }
; __device__ __forceinline__ void hyena_prep(const bf16_t* __restrict__ PA, const float* __restrict__ cb  , bf16_t* ZT0, bf16_t* G1T, bf16_t* G2T) {
;     ...
;     for (int task = blockIdx.x; task < 768; task += gridDim.x) {
;         const int arr = task >> 8, t0 = (task & 255) * 64;
;         const float w0 = cb[(arr * 3 + 0) * 512 + c], w1 = cb[(arr * 3 + 1) * 512 + c], w2 = cb[(arr * 3 + 2) * 512 + c];
;         const bf16_t* src = PA + 1536 + arr * 512 + c;
;         bf16_t* dst = (arr == 0 ? ZT0 : (arr == 1 ? G1T : G2T)) + (size_t)c * L_ + t0;
;         bf16_t raw[66];
; #pragma unroll
;         for (int k = 0; k < 66; ++k) { const int tt = t0 - 1 + k; raw[k] = (tt >= 0 && tt < L_) ? src[(size_t)tt * 3072] : (bf16_t)0; }
;     ...
;         for (int i8 = 0; i8 < 8; ++i8) {
;             float o[8];
; #pragma unroll
;             for (int k = 0; k < 8; ++k) o[k] = w0 * bf2f(raw[i8 * 8 + k]) + w1 * bf2f(raw[i8 * 8 + k + 1]) + w2 * bf2f(raw[i8 * 8 + k + 2]);
;             u32x4 w; w.x = pk2(o[0], o[1]); w.y = pk2(o[2], o[3]); w.z = pk2(o[4], o[5]); w.w = pk2(o[6], o[7]);
;             *(u32x4*)(dst + i8 * 8) = w;
;         }
	s_nop 0
	v_lshlrev_b32_e32 v17, 16, v69
	v_lshlrev_b32_e32 v16, 16, v68
	v_pk_mov_b32 v[12:13], v[12:13], v[16:17] op_sel:[1,0]
	v_lshlrev_b32_e32 v18, 16, v61
	v_pk_mul_f32 v[12:13], v[8:9], v[12:13]
	s_waitcnt vmcnt(17)
	v_lshlrev_b32_e32 v19, 16, v62
	v_fma_f32 v1, v6, v21, v12
	v_add_f32_e32 v1, v1, v13
	v_pk_mul_f32 v[12:13], v[8:9], v[16:17]
	v_pk_mov_b32 v[20:21], v[20:21], v[18:19] op_sel:[1,0]
	v_fma_f32 v12, v6, v18, v12
	v_add_f32_e32 v24, v12, v13
	v_pk_mul_f32 v[12:13], v[8:9], v[18:19]
	v_pk_mul_f32 v[20:21], v[8:9], v[20:21]
	v_fma_f32 v12, v6, v17, v12
	v_add_f32_e32 v18, v12, v13
	s_waitcnt vmcnt(14)
	v_lshlrev_b32_e32 v13, 16, v55
	v_lshlrev_b32_e32 v12, 16, v50
	v_fma_f32 v10, v6, v16, v20
	v_pk_mov_b32 v[16:17], v[16:17], v[12:13] op_sel:[1,0]
	v_lshlrev_b32_e32 v20, 16, v44
	v_pk_mul_f32 v[16:17], v[8:9], v[16:17]
	v_mov_b32_e32 v22, v12
	v_fma_f32 v16, v6, v19, v16
	v_add_f32_e32 v25, v16, v17
	v_pk_mul_f32 v[16:17], v[8:9], v[12:13]
	v_mov_b32_e32 v23, v20
	v_add_f32_e32 v10, v10, v21
	s_waitcnt vmcnt(13)
	v_lshlrev_b32_e32 v21, 16, v76
	v_pk_mul_f32 v[22:23], v[6:7], v[22:23]
	v_fma_f32 v16, v6, v20, v16
	v_fma_f32 v19, v8, v19, v22
	v_add_f32_e32 v22, v16, v17
	v_pk_mul_f32 v[16:17], v[8:9], v[20:21]
	v_add_f32_e32 v19, v19, v23
	v_fma_f32 v16, v6, v13, v16
	v_add_f32_e32 v20, v16, v17
	v_cvt_pk_bf16_f32 v16, v1, v10
	v_cvt_pk_bf16_f32 v17, v24, v18
	v_cvt_pk_bf16_f32 v18, v25, v19
	v_cvt_pk_bf16_f32 v19, v22, v20
	s_waitcnt vmcnt(10)
	v_lshlrev_b32_e32 v23, 16, v72
	v_lshlrev_b32_e32 v22, 16, v70
	v_pk_mov_b32 v[12:13], v[12:13], v[22:23] op_sel:[1,0]
	global_store_dwordx4 v[14:15], v[16:19], off offset:96
	v_pk_mul_f32 v[12:13], v[8:9], v[12:13]
	s_nop 0
	v_lshlrev_b32_e32 v17, 16, v73
	v_mov_b32_e32 v16, v21
	v_pk_mul_f32 v[18:19], v[8:9], v[16:17]
	v_fma_f32 v1, v6, v21, v12
	v_add_f32_e32 v1, v1, v13
	v_fma_f32 v10, v6, v22, v18
	v_pk_mul_f32 v[12:13], v[8:9], v[22:23]
	v_add_f32_e32 v24, v10, v19
	v_fma_f32 v10, v6, v17, v12
	v_add_f32_e32 v25, v10, v13
	s_waitcnt vmcnt(10)
	v_lshlrev_b32_e32 v12, 16, v64
	s_waitcnt vmcnt(8)
	v_lshlrev_b32_e32 v13, 16, v66
	v_pk_mov_b32 v[18:19], v[22:23], v[12:13] op_sel:[1,0]
	s_nop 0
	v_pk_mul_f32 v[18:19], v[6:7], v[18:19]
	s_nop 0
	v_fma_f32 v7, v8, v17, v18
	v_add_f32_e32 v7, v7, v19
	v_lshlrev_b32_e32 v18, 16, v56
	s_waitcnt vmcnt(7)
	v_lshlrev_b32_e32 v19, 16, v58
	v_pk_mov_b32 v[20:21], v[22:23], v[18:19] op_sel:[1,0]
	v_pk_mul_f32 v[16:17], v[8:9], v[12:13]
	v_pk_mul_f32 v[20:21], v[8:9], v[20:21]
	s_nop 0
	v_fma_f32 v10, v6, v12, v20
	v_add_f32_e32 v12, v10, v21
	v_fma_f32 v10, v6, v18, v16
	v_add_f32_e32 v20, v10, v17
	v_pk_mul_f32 v[16:17], v[8:9], v[18:19]
	s_nop 0
	v_fma_f32 v10, v6, v13, v16
	v_add_f32_e32 v16, v10, v17
	v_mov_b32_e32 v10, v13
	v_pk_mul_f32 v[8:9], v[8:9], v[10:11]
	s_nop 0
	v_fma_f32 v6, v6, v19, v8
	v_add_f32_e32 v9, v6, v9
	v_cvt_pk_bf16_f32 v6, v1, v24
	v_cvt_pk_bf16_f32 v7, v25, v7
	v_cvt_pk_bf16_f32 v8, v12, v20
	v_cvt_pk_bf16_f32 v9, v16, v9
	global_store_dwordx4 v[14:15], v[6:9], off offset:112
	s_cbranch_scc0 .LBB0_220
.LBB0_216:
	s_ashr_i32 s2, s1, 8
	s_mul_i32 s3, s2, 0x600
	v_add_u32_e32 v6, s3, v0
	v_readlane_b32 s4, v246, 25
	v_ashrrev_i32_e32 v7, 31, v6
	v_readlane_b32 s5, v246, 26
	v_add_u32_e32 v10, 0x200, v6
	v_ashrrev_i32_e32 v11, 31, v10
	v_lshl_add_u64 v[8:9], v[6:7], 2, s[4:5]
	v_add_u32_e32 v6, 0x400, v6
	v_ashrrev_i32_e32 v7, 31, v6
	v_lshl_add_u64 v[10:11], v[10:11], 2, s[4:5]
	v_lshl_add_u64 v[12:13], v[6:7], 2, s[4:5]
	global_load_dword v8, v[8:9], off
	s_nop 0
	global_load_dword v6, v[10:11], off
	global_load_dword v9, v[12:13], off
	s_lshl_b32 s4, s2, 9
	s_and_b32 s3, s0, 0x3fc0
	s_ashr_i32 s5, s4, 31
	v_lshl_add_u64 v[14:15], s[4:5], 1, v[2:3]
	s_add_i32 s4, s3, -1
	v_mov_b32_e32 v11, 0
	s_cmpk_gt_u32 s4, 0x3fff
	v_mov_b32_e32 v12, 0
	v_mov_b32_e32 v243, 0
	s_cbranch_scc1 .LBB0_218
	s_mul_i32 s20, s4, 0xc00
	v_lshl_add_u64 v[12:13], s[20:21], 1, v[14:15]
	global_load_ushort v243, v[12:13], off
